# SSM pass 3: next item's u fragments prefetched during the current item (software pipelining of the per-item input loads)
# speedup vs baseline: 1.2524x; 1.0060x over previous
.LBB0_381:
	v_lshrrev_b32_e32 v0, 11, v120
	v_bfe_u32 v1, v120, 3, 8
	v_mad_u32_u24 v0, v1, 12, v0
	v_and_b32_e32 v122, 63, v0
	v_lshrrev_b32_e32 v1, 6, v0
	v_mul_u32_u24_e32 v2, 0x2ab, v1
	v_lshrrev_b32_e32 v121, 13, v2
	v_mul_u32_u24_e32 v2, 12, v121
	v_sub_u32_e32 v1, v1, v2
	v_and_b32_e32 v3, 7, v120
	v_lshl_or_b32 v108, v1, 3, v3
	v_lshlrev_b32_e32 v0, 12, v121
	v_lshl_add_u32 v124, v122, 6, v0
	v_lshlrev_b32_e32 v68, 4, v108
	v_or_b32_e32 v0, v124, v198
	v_ashrrev_i32_e32 v69, 31, v68
	v_lshl_add_u64 v[70:71], v[68:69], 1, s[26:27]
	v_ashrrev_i32_e32 v1, 31, v0
	v_or_b32_e32 v6, 16, v0
	v_lshl_add_u64 v[2:3], v[70:71], 0, v[106:107]
	v_lshlrev_b64 v[4:5], 13, v[0:1]
	v_ashrrev_i32_e32 v7, 31, v6
	v_lshl_add_u64 v[4:5], v[2:3], 0, v[4:5]
	v_lshlrev_b64 v[6:7], 13, v[6:7]
	v_lshl_add_u64 v[6:7], v[2:3], 0, v[6:7]
	v_readfirstlane_b32 s61, v120
	s_cmp_lt_u32 s61, 0x800
	s_cbranch_scc0 .Lp3_pf_mov0
	global_load_dwordx4 v[64:67], v[4:5], off
	global_load_dwordx4 v[60:63], v[6:7], off
	s_branch .Lp3_pf_j0
.Lp3_pf_mov0:
	s_waitcnt vmcnt(16)
	v_mov_b32_e32 v64, v176
	v_mov_b32_e32 v65, v177
	v_mov_b32_e32 v66, v178
	v_mov_b32_e32 v67, v179
	v_mov_b32_e32 v60, v180
	v_mov_b32_e32 v61, v181
	v_mov_b32_e32 v62, v182
	v_mov_b32_e32 v63, v183
.Lp3_pf_j0:
	v_or_b32_e32 v4, 32, v0
	v_or_b32_e32 v0, 48, v0
	v_ashrrev_i32_e32 v5, 31, v4
	v_ashrrev_i32_e32 v1, 31, v0
	v_lshlrev_b64 v[4:5], 13, v[4:5]
	v_lshlrev_b64 v[0:1], 13, v[0:1]
	v_lshl_add_u64 v[4:5], v[2:3], 0, v[4:5]
	v_lshl_add_u64 v[0:1], v[2:3], 0, v[0:1]
	v_ashrrev_i32_e32 v109, 31, v108
	s_cbranch_scc0 .Lp3_pf_mov1
	global_load_dwordx4 v[56:59], v[4:5], off
	global_load_dwordx4 v[20:23], v[0:1], off
	s_branch .Lp3_pf_j1
.Lp3_pf_mov1:
	v_mov_b32_e32 v56, v184
	v_mov_b32_e32 v57, v185
	v_mov_b32_e32 v58, v186
	v_mov_b32_e32 v59, v187
	v_mov_b32_e32 v20, v188
	v_mov_b32_e32 v21, v189
	v_mov_b32_e32 v22, v190
	v_mov_b32_e32 v23, v191
.Lp3_pf_j1:
	v_lshlrev_b64 v[0:1], 10, v[108:109]
	v_lshl_add_u64 v[0:1], v[78:79], 0, v[0:1]
	v_lshlrev_b64 v[2:3], 13, v[108:109]
	v_lshl_add_u64 v[4:5], v[80:81], 0, v[2:3]
	global_load_dwordx4 v[8:11], v[0:1], off
	global_load_dwordx4 v[52:55], v[4:5], off
	v_lshl_add_u64 v[0:1], v[82:83], 0, v[2:3]
	v_lshl_add_u64 v[4:5], v[84:85], 0, v[2:3]
	global_load_dwordx4 v[48:51], v[0:1], off
	global_load_dwordx4 v[44:47], v[4:5], off
	v_lshl_add_u64 v[0:1], v[86:87], 0, v[2:3]
	v_lshl_add_u64 v[4:5], v[88:89], 0, v[2:3]
	global_load_dwordx4 v[40:43], v[0:1], off
	global_load_dwordx4 v[36:39], v[4:5], off
	v_lshl_add_u64 v[0:1], v[90:91], 0, v[2:3]
	v_lshl_add_u64 v[4:5], v[92:93], 0, v[2:3]
	global_load_dwordx4 v[32:35], v[0:1], off
	global_load_dwordx4 v[28:31], v[4:5], off
	v_lshl_add_u64 v[0:1], v[94:95], 0, v[2:3]
	v_lshlrev_b64 v[2:3], 12, v[108:109]
	v_lshl_add_u64 v[2:3], v[96:97], 0, v[2:3]
	global_load_dwordx4 v[24:27], v[0:1], off
	global_load_dwordx4 v[16:19], v[2:3], off
	global_load_dwordx4 v[12:15], v[2:3], off offset:1024
	global_load_dwordx4 v[4:7], v[2:3], off offset:2048
	s_nop 0
	global_load_dwordx4 v[0:3], v[2:3], off offset:3072
	v_or_b32_e32 v110, v68, v198
	v_ashrrev_i32_e32 v111, 31, v110
	v_lshl_add_u64 v[110:111], v[110:111], 2, s[58:59]
	global_load_dword v123, v[110:111], off
	v_or_b32_e32 v170, v124, v235
	v_mov_b32_e32 v171, 0
	v_lshl_add_u64 v[168:169], v[70:71], 0, v[74:75]
	v_lshlrev_b64 v[170:171], 13, v[170:171]
	s_mov_b64 s[60:61], 0x2000
	s_mov_b64 s[40:41], 0x20000
	v_lshl_add_u64 v[168:169], v[168:169], 0, v[170:171]
	v_lshl_add_u64 v[170:171], v[168:169], 0, s[60:61]
	v_lshl_add_u64 v[172:173], v[170:171], 0, s[60:61]
	v_lshl_add_u64 v[174:175], v[172:173], 0, s[60:61]
	global_load_ushort v152, v[168:169], off
	global_load_ushort v153, v[170:171], off
	global_load_ushort v154, v[172:173], off
	global_load_ushort v155, v[174:175], off
	v_lshl_add_u64 v[168:169], v[168:169], 0, s[40:41]
	v_lshl_add_u64 v[170:171], v[168:169], 0, s[60:61]
	v_lshl_add_u64 v[172:173], v[170:171], 0, s[60:61]
	v_lshl_add_u64 v[174:175], v[172:173], 0, s[60:61]
	global_load_ushort v156, v[168:169], off
	global_load_ushort v157, v[170:171], off
	global_load_ushort v158, v[172:173], off
	global_load_ushort v159, v[174:175], off
	v_lshl_add_u64 v[168:169], v[168:169], 0, s[40:41]
	v_lshl_add_u64 v[170:171], v[168:169], 0, s[60:61]
	v_lshl_add_u64 v[172:173], v[170:171], 0, s[60:61]
	v_lshl_add_u64 v[174:175], v[172:173], 0, s[60:61]
	global_load_ushort v160, v[168:169], off
	global_load_ushort v161, v[170:171], off
	global_load_ushort v162, v[172:173], off
	global_load_ushort v163, v[174:175], off
	v_lshl_add_u64 v[168:169], v[168:169], 0, s[40:41]
	v_lshl_add_u64 v[170:171], v[168:169], 0, s[60:61]
	v_lshl_add_u64 v[172:173], v[170:171], 0, s[60:61]
	v_lshl_add_u64 v[174:175], v[172:173], 0, s[60:61]
	global_load_ushort v164, v[168:169], off
	global_load_ushort v165, v[170:171], off
	global_load_ushort v166, v[172:173], off
	global_load_ushort v167, v[174:175], off
	v_readfirstlane_b32 s60, v120
	s_cmp_lt_u32 s60, 0x800
	s_cbranch_scc1 .Lp3_horner
	v_cmp_ne_u32_e32 vcc, 0, v122
	s_nop 1
	v_cndmask_b32_e32 v125, 0, v254, vcc
	v_cndmask_b32_e32 v111, 0, v255, vcc
	s_branch .Lp3_after_horner

.Lp3_after_horner:
	s_waitcnt vmcnt(28)
	v_mfma_f32_16x16x32_bf16 v[112:115], v[64:67], v[52:55], 0
	s_waitcnt vmcnt(27)
	v_mfma_f32_16x16x32_bf16 v[126:129], v[64:67], v[48:51], 0
	s_waitcnt vmcnt(26)
	v_mfma_f32_16x16x32_bf16 v[130:133], v[64:67], v[44:47], 0
	s_nop 3
	ds_write_b128 v73, v[112:115]
	s_waitcnt vmcnt(25)
	v_mfma_f32_16x16x32_bf16 v[134:137], v[64:67], v[40:43], 0
	ds_write_b128 v73, v[126:129] offset:1280
	ds_write_b128 v73, v[130:133] offset:2560
	s_nop 5
	ds_write_b128 v73, v[134:137] offset:3840
	s_waitcnt vmcnt(24)
	v_mfma_f32_16x16x32_bf16 v[138:141], v[64:67], v[36:39], 0
	s_waitcnt vmcnt(23)
	v_mfma_f32_16x16x32_bf16 v[112:115], v[64:67], v[32:35], 0
	s_waitcnt vmcnt(22)
	v_mfma_f32_16x16x32_bf16 v[126:129], v[64:67], v[28:31], 0
	s_nop 3
	ds_write_b128 v73, v[138:141] offset:5120
	s_nop 0
	ds_write_b128 v73, v[112:115] offset:6400
	s_nop 0
	ds_write_b128 v73, v[126:129] offset:7680
	s_waitcnt vmcnt(21)
	v_mfma_f32_16x16x32_bf16 v[64:67], v[64:67], v[24:27], 0
	v_mfma_f32_16x16x32_bf16 v[136:139], v[60:63], v[44:47], 0
	s_nop 6
	ds_write_b128 v73, v[64:67] offset:8960
	v_add_u32_e32 v168, 0x800, v120
	v_min_u32_e32 v168, 0x5fff, v168
	v_lshrrev_b32_e32 v169, 11, v168
	v_bfe_u32 v170, v168, 3, 8
	v_mad_u32_u24 v169, v170, 12, v169
	v_and_b32_e32 v171, 63, v169
	v_lshrrev_b32_e32 v170, 6, v169
	v_mul_u32_u24_e32 v172, 0x2ab, v170
	v_lshrrev_b32_e32 v172, 13, v172
	v_mul_u32_u24_e32 v173, 12, v172
	v_sub_u32_e32 v170, v170, v173
	v_and_b32_e32 v173, 7, v168
	v_lshl_or_b32 v170, v170, 3, v173
	v_lshlrev_b32_e32 v172, 12, v172
	v_lshl_add_u32 v171, v171, 6, v172
	v_or_b32_e32 v171, v171, v198
	v_lshlrev_b32_e32 v172, 5, v170
	v_add_u32_e32 v172, v172, v106
	v_mov_b32_e32 v173, 0
	v_lshl_add_u64 v[172:173], s[26:27], 0, v[172:173]
	v_lshlrev_b32_e32 v174, 13, v171
	v_mov_b32_e32 v175, 0
	v_lshl_add_u64 v[172:173], v[172:173], 0, v[174:175]
	s_mov_b64 s[60:61], 0x20000
	global_load_dwordx4 v[176:179], v[172:173], off
	v_lshl_add_u64 v[174:175], v[172:173], 0, s[60:61]
	global_load_dwordx4 v[180:183], v[174:175], off
	v_lshl_add_u64 v[192:193], v[174:175], 0, s[60:61]
	global_load_dwordx4 v[184:187], v[192:193], off
	v_lshl_add_u64 v[194:195], v[192:193], 0, s[60:61]
	global_load_dwordx4 v[188:191], v[194:195], off
	ds_read_b128 v[64:67], v77
	ds_read_b128 v[112:115], v77 offset:80
	s_waitcnt lgkmcnt(1)
	v_fma_f32 v10, -v9, v111, v64
	s_waitcnt lgkmcnt(0)
	v_fma_f32 v11, v9, v125, v112
	v_fmac_f32_e32 v10, v8, v125
	v_fmac_f32_e32 v11, v8, v111
	s_nop 0
	v_cvt_pk_bf16_f32 v64, v10, v11
	ds_write_b32 v118, v64 offset:10240
	v_fma_f32 v64, -v9, v11, v65
	v_fmac_f32_e32 v64, v8, v10
	v_fma_f32 v10, v9, v10, v113
	v_fmac_f32_e32 v10, v8, v11
	s_nop 0
	v_cvt_pk_bf16_f32 v11, v64, v10
	ds_write_b32 v118, v11 offset:10512
	v_fma_f32 v11, -v9, v10, v66
	v_fmac_f32_e32 v11, v8, v64
	v_fma_f32 v64, v9, v64, v114
	v_fmac_f32_e32 v64, v8, v10
	s_nop 0
	v_cvt_pk_bf16_f32 v10, v11, v64
	ds_write_b32 v118, v10 offset:10784
	v_fma_f32 v10, -v9, v64, v67
	v_fmac_f32_e32 v115, v9, v11
	v_fmac_f32_e32 v10, v8, v11
	v_fmac_f32_e32 v115, v8, v64
	s_nop 0
	v_cvt_pk_bf16_f32 v11, v10, v115
	ds_write_b32 v118, v11 offset:11056
	ds_read_b128 v[64:67], v77 offset:16
	ds_read_b128 v[110:113], v77 offset:96
	s_waitcnt lgkmcnt(1)
	v_fma_f32 v11, -v9, v115, v64
	v_fmac_f32_e32 v11, v8, v10
	s_waitcnt lgkmcnt(0)
	v_fma_f32 v10, v9, v10, v110
	v_fmac_f32_e32 v10, v8, v115
	s_nop 0
	v_cvt_pk_bf16_f32 v64, v11, v10
	ds_write_b32 v118, v64 offset:11328
	v_fma_f32 v64, -v9, v10, v65
	v_fmac_f32_e32 v64, v8, v11
	v_fma_f32 v11, v9, v11, v111
	v_fmac_f32_e32 v11, v8, v10
	s_nop 0
	v_cvt_pk_bf16_f32 v10, v64, v11
	ds_write_b32 v118, v10 offset:11600
	v_fma_f32 v10, -v9, v11, v66
	v_fmac_f32_e32 v10, v8, v64
	v_fma_f32 v64, v9, v64, v112
	v_fmac_f32_e32 v64, v8, v11
	s_nop 0
	v_cvt_pk_bf16_f32 v11, v10, v64
	ds_write_b32 v118, v11 offset:11872
	v_fma_f32 v11, -v9, v64, v67
	v_fmac_f32_e32 v113, v9, v10
	v_fmac_f32_e32 v11, v8, v10
	v_fmac_f32_e32 v113, v8, v64
	s_nop 0
	v_cvt_pk_bf16_f32 v10, v11, v113
	ds_write_b32 v118, v10 offset:12144
	ds_read_b128 v[64:67], v77 offset:32
	ds_read_b128 v[126:129], v77 offset:112
	s_waitcnt lgkmcnt(1)
	v_fma_f32 v10, -v9, v113, v64
	v_fmac_f32_e32 v10, v8, v11
	s_waitcnt lgkmcnt(0)
	v_fma_f32 v11, v9, v11, v126
	v_fmac_f32_e32 v11, v8, v113
	s_nop 0
	v_cvt_pk_bf16_f32 v64, v10, v11
	ds_write_b32 v118, v64 offset:12416
	v_fma_f32 v64, -v9, v11, v65
	v_fmac_f32_e32 v64, v8, v10
	v_fma_f32 v10, v9, v10, v127
	v_fmac_f32_e32 v10, v8, v11
	s_nop 0
	v_cvt_pk_bf16_f32 v11, v64, v10
	ds_write_b32 v118, v11 offset:12688
	v_fma_f32 v11, -v9, v10, v66
	v_fmac_f32_e32 v11, v8, v64
	v_fma_f32 v64, v9, v64, v128
	v_fmac_f32_e32 v64, v8, v10
	s_nop 0
	v_cvt_pk_bf16_f32 v10, v11, v64
	ds_write_b32 v118, v10 offset:12960
	v_fma_f32 v10, -v9, v64, v67
	v_fmac_f32_e32 v129, v9, v11
	v_fmac_f32_e32 v10, v8, v11
	v_fmac_f32_e32 v129, v8, v64
	s_nop 0
	v_cvt_pk_bf16_f32 v11, v10, v129
	ds_write_b32 v118, v11 offset:13232
	ds_read_b128 v[110:113], v77 offset:48
	ds_read_b128 v[64:67], v77 offset:128
	s_waitcnt lgkmcnt(1)
	v_fma_f32 v11, -v9, v129, v110
	v_fmac_f32_e32 v11, v8, v10
	s_waitcnt lgkmcnt(0)
	v_fma_f32 v10, v9, v10, v64
	v_fmac_f32_e32 v10, v8, v129
	s_nop 0
	v_cvt_pk_bf16_f32 v64, v11, v10
	ds_write_b32 v118, v64 offset:13504
	v_fma_f32 v64, -v9, v10, v111
	v_fmac_f32_e32 v64, v8, v11
	v_fma_f32 v11, v9, v11, v65
	v_fmac_f32_e32 v11, v8, v10
	s_nop 0
	v_cvt_pk_bf16_f32 v10, v64, v11
	ds_write_b32 v118, v10 offset:13776
	v_fma_f32 v10, -v9, v11, v112
	v_fmac_f32_e32 v10, v8, v64
	v_fma_f32 v64, v9, v64, v66
	v_fmac_f32_e32 v64, v8, v11
	s_nop 0
	v_fma_f32 v66, -v9, v64, v113
	v_fmac_f32_e32 v67, v9, v10
	v_cvt_pk_bf16_f32 v11, v10, v64
	v_fmac_f32_e32 v66, v8, v10
	v_fmac_f32_e32 v67, v8, v64
	ds_write_b32 v118, v11 offset:14048
	s_nop 0
	v_cvt_pk_bf16_f32 v10, v66, v67
	ds_write_b32 v118, v10 offset:14320
	ds_read_b128 v[110:113], v119 offset:10240
	ds_read_b128 v[126:129], v119 offset:10304
	s_waitcnt vmcnt(20) lgkmcnt(1)
	v_mfma_f32_16x16x32_bf16 v[112:115], v[110:113], v[16:19], 0
	v_or_b32_e32 v110, v124, v235
	v_ashrrev_i32_e32 v111, 31, v110
	v_lshl_add_u64 v[10:11], v[70:71], 0, v[74:75]
	v_lshlrev_b64 v[64:65], 13, v[110:111]
	v_lshl_add_u64 v[64:65], v[10:11], 0, v[64:65]
	ds_read_b128 v[132:135], v119 offset:10368
	ds_read_b128 v[140:143], v119 offset:10432
	s_waitcnt vmcnt(19) lgkmcnt(2)
	v_mfma_f32_16x16x32_bf16 v[112:115], v[126:129], v[12:15], v[112:115]
	s_waitcnt vmcnt(15)
	v_lshlrev_b32_e32 v109, 16, v152
	s_waitcnt lgkmcnt(1)
	v_mfma_f32_16x16x32_bf16 v[132:135], v[132:135], v[4:7], v[112:115]
	s_nop 3
	v_lshl_add_u64 v[112:113], v[68:69], 1, v[98:99]
	s_waitcnt lgkmcnt(0)
	v_mfma_f32_16x16x32_bf16 v[68:71], v[140:143], v[0:3], v[132:135]
	v_or_b32_e32 v114, 1, v110
	v_ashrrev_i32_e32 v115, 31, v114
	v_mad_i64_i32 v[64:65], s[38:39], v110, s56, v[112:113]
	v_lshlrev_b64 v[132:133], 13, v[114:115]
	s_nop 3
	v_fma_f32 v68, v123, v109, v68
	v_mul_f32_e32 v109, 0x3d372713, v68
	v_mul_f32_e32 v109, v68, v109
	v_fma_f32 v109, v68, v109, v68
	v_mul_f32_e32 v109, 0xbfcc422a, v109
	v_mul_f32_e32 v109, 0x3fb8aa3b, v109
	v_exp_f32_e32 v109, v109
	v_lshl_add_u64 v[140:141], v[10:11], 0, v[132:133]
	v_mfma_f32_16x16x32_bf16 v[124:127], v[60:63], v[52:55], 0
	v_add_f32_e32 v109, 1.0, v109
	v_div_scale_f32 v111, s[38:39], v109, v109, v68
	v_rcp_f32_e32 v115, v111
	v_div_scale_f32 v132, vcc, v68, v109, v68
	v_mfma_f32_16x16x32_bf16 v[128:131], v[60:63], v[48:51], 0
	v_fma_f32 v133, -v111, v115, 1.0
	v_fmac_f32_e32 v115, v133, v115
	v_mul_f32_e32 v133, v132, v115
	v_fma_f32 v134, -v111, v133, v132
	v_fmac_f32_e32 v133, v134, v115
	v_fma_f32 v111, -v111, v133, v132
	v_div_fmas_f32 v111, v111, v115, v133
	v_div_fixup_f32 v68, v111, v109, v68
	v_cvt_pk_bf16_f32 v68, v68, s0
	global_store_short v[64:65], v68, off
	v_or_b32_e32 v64, 2, v110
	v_mfma_f32_16x16x32_bf16 v[132:135], v[60:63], v[40:43], 0
	s_waitcnt vmcnt(15)
	v_lshlrev_b32_e32 v65, 16, v153
	v_fma_f32 v109, v123, v65, v69
	v_mul_f32_e32 v65, 0x3d372713, v109
	v_mul_f32_e32 v65, v109, v65
	v_fma_f32 v65, v109, v65, v109
	v_mul_f32_e32 v65, 0xbfcc422a, v65
	v_mul_f32_e32 v65, 0x3fb8aa3b, v65
	v_exp_f32_e32 v111, v65
	v_ashrrev_i32_e32 v65, 31, v64
	v_mad_i64_i32 v[68:69], s[38:39], v114, s56, v[112:113]
	v_lshlrev_b64 v[114:115], 13, v[64:65]
	v_add_f32_e32 v65, 1.0, v111
	v_div_scale_f32 v111, s[38:39], v65, v65, v109
	v_rcp_f32_e32 v144, v111
	v_div_scale_f32 v145, vcc, v109, v65, v109
	v_lshl_add_u64 v[114:115], v[10:11], 0, v[114:115]
	v_fma_f32 v146, -v111, v144, 1.0
	v_fmac_f32_e32 v144, v146, v144
	v_mul_f32_e32 v146, v145, v144
	v_fma_f32 v147, -v111, v146, v145
	v_fmac_f32_e32 v146, v147, v144
	v_fma_f32 v111, -v111, v146, v145
	v_div_fmas_f32 v111, v111, v144, v146
	v_div_fixup_f32 v65, v111, v65, v109
	v_cvt_pk_bf16_f32 v65, v65, s0
	global_store_short v[68:69], v65, off
	v_or_b32_e32 v68, 3, v110
	v_ashrrev_i32_e32 v69, 31, v68
	v_lshlrev_b64 v[114:115], 13, v[68:69]
	v_lshl_add_u64 v[114:115], v[10:11], 0, v[114:115]
	v_mfma_f32_16x16x32_bf16 v[140:143], v[60:63], v[36:39], 0
	s_waitcnt vmcnt(15)
	v_lshlrev_b32_e32 v65, 16, v154
	v_fma_f32 v70, v123, v65, v70
	v_mul_f32_e32 v65, 0x3d372713, v70
	v_mul_f32_e32 v65, v70, v65
	v_fma_f32 v65, v70, v65, v70
	v_mul_f32_e32 v65, 0xbfcc422a, v65
	v_mul_f32_e32 v65, 0x3fb8aa3b, v65
	v_exp_f32_e32 v109, v65
	v_mad_i64_i32 v[64:65], s[38:39], v64, s56, v[112:113]
	v_mfma_f32_16x16x32_bf16 v[144:147], v[60:63], v[32:35], 0
	v_add_f32_e32 v69, 1.0, v109
	v_div_scale_f32 v109, s[38:39], v69, v69, v70
	v_rcp_f32_e32 v111, v109
	v_div_scale_f32 v148, vcc, v70, v69, v70
	v_fma_f32 v149, -v109, v111, 1.0
	v_fmac_f32_e32 v111, v149, v111
	v_mul_f32_e32 v149, v148, v111
	v_fma_f32 v150, -v109, v149, v148
	v_fmac_f32_e32 v149, v150, v111
	v_fma_f32 v109, -v109, v149, v148
	v_div_fmas_f32 v109, v109, v111, v149
	v_div_fixup_f32 v69, v109, v69, v70
	v_cvt_pk_bf16_f32 v69, v69, s0
	global_store_short v[64:65], v69, off
	v_mfma_f32_16x16x32_bf16 v[148:151], v[60:63], v[28:31], 0
	s_waitcnt vmcnt(15)
	v_lshlrev_b32_e32 v64, 16, v155
	v_fmac_f32_e32 v71, v123, v64
	v_mul_f32_e32 v64, 0x3d372713, v71
	v_mul_f32_e32 v64, v71, v64
	v_fma_f32 v64, v71, v64, v71
	v_mul_f32_e32 v64, 0xbfcc422a, v64
	v_mul_f32_e32 v64, 0x3fb8aa3b, v64
	v_exp_f32_e32 v64, v64
	v_mfma_f32_16x16x32_bf16 v[60:63], v[60:63], v[24:27], 0
	v_add_f32_e32 v69, 1.0, v64
	v_div_scale_f32 v70, s[38:39], v69, v69, v71
	v_rcp_f32_e32 v109, v70
	v_mad_i64_i32 v[64:65], s[38:39], v68, s56, v[112:113]
	v_div_scale_f32 v68, vcc, v71, v69, v71
	v_fma_f32 v111, -v70, v109, 1.0
	v_fmac_f32_e32 v109, v111, v109
	v_mul_f32_e32 v111, v68, v109
	v_fma_f32 v114, -v70, v111, v68
	v_fmac_f32_e32 v111, v114, v109
	v_fma_f32 v68, -v70, v111, v68
	v_div_fmas_f32 v68, v68, v109, v111
	v_div_fixup_f32 v68, v68, v69, v71
	v_cvt_pk_bf16_f32 v68, v68, s0
	global_store_short v[64:65], v68, off
	ds_write_b128 v73, v[124:127]
	ds_write_b128 v73, v[128:131] offset:1280
	ds_write_b128 v73, v[136:139] offset:2560
	ds_write_b128 v73, v[132:135] offset:3840
	ds_write_b128 v73, v[140:143] offset:5120
	ds_write_b128 v73, v[144:147] offset:6400
	ds_write_b128 v73, v[148:151] offset:7680
	ds_write_b128 v73, v[60:63] offset:8960
	ds_read_b128 v[68:71], v77
	ds_read_b128 v[60:63], v77 offset:80
	v_mfma_f32_16x16x32_bf16 v[124:127], v[56:59], v[52:55], 0
	s_waitcnt lgkmcnt(1)
	v_fma_f32 v64, -v9, v67, v68
	s_waitcnt lgkmcnt(0)
	v_fma_f32 v60, v9, v66, v60
	v_fmac_f32_e32 v64, v8, v66
	v_fmac_f32_e32 v60, v8, v67
	v_mfma_f32_16x16x32_bf16 v[128:131], v[56:59], v[48:51], 0
	v_fma_f32 v66, -v9, v60, v69
	v_fma_f32 v61, v9, v64, v61
	v_cvt_pk_bf16_f32 v65, v64, v60
	v_fmac_f32_e32 v66, v8, v64
	v_fmac_f32_e32 v61, v8, v60
	ds_write_b32 v118, v65 offset:10240
	v_mfma_f32_16x16x32_bf16 v[132:135], v[56:59], v[44:47], 0
	v_fma_f32 v64, -v9, v61, v70
	v_fma_f32 v62, v9, v66, v62
	v_cvt_pk_bf16_f32 v60, v66, v61
	v_fmac_f32_e32 v64, v8, v66
	v_fmac_f32_e32 v62, v8, v61
	ds_write_b32 v118, v60 offset:10512
	v_mfma_f32_16x16x32_bf16 v[52:55], v[20:23], v[52:55], 0
	v_fma_f32 v61, -v9, v62, v71
	v_fmac_f32_e32 v63, v9, v64
	v_cvt_pk_bf16_f32 v60, v64, v62
	v_fmac_f32_e32 v61, v8, v64
	v_fmac_f32_e32 v63, v8, v62
	ds_write_b32 v118, v60 offset:10784
	v_mfma_f32_16x16x32_bf16 v[48:51], v[20:23], v[48:51], 0
	v_cvt_pk_bf16_f32 v60, v61, v63
	ds_write_b32 v118, v60 offset:11056
	ds_read_b128 v[68:71], v77 offset:16
	ds_read_b128 v[64:67], v77 offset:96
	v_mfma_f32_16x16x32_bf16 v[44:47], v[20:23], v[44:47], 0
	s_waitcnt lgkmcnt(1)
	v_fma_f32 v60, -v9, v63, v68
	s_waitcnt lgkmcnt(0)
	v_fma_f32 v62, v9, v61, v64
	v_fmac_f32_e32 v60, v8, v61
	v_fmac_f32_e32 v62, v8, v63
	s_nop 0
	v_fma_f32 v63, -v9, v62, v69
	v_fma_f32 v64, v9, v60, v65
	v_cvt_pk_bf16_f32 v61, v60, v62
	v_fmac_f32_e32 v63, v8, v60
	v_fmac_f32_e32 v64, v8, v62
	ds_write_b32 v118, v61 offset:11328
	s_nop 0
	v_fma_f32 v61, -v9, v64, v70
	v_fma_f32 v62, v9, v63, v66
	v_cvt_pk_bf16_f32 v60, v63, v64
	v_fmac_f32_e32 v61, v8, v63
	v_fmac_f32_e32 v62, v8, v64
	ds_write_b32 v118, v60 offset:11600
	s_nop 0
	v_fma_f32 v64, -v9, v62, v71
	v_fmac_f32_e32 v67, v9, v61
	v_cvt_pk_bf16_f32 v60, v61, v62
	v_fmac_f32_e32 v64, v8, v61
	v_fmac_f32_e32 v67, v8, v62
	ds_write_b32 v118, v60 offset:11872
	s_nop 0
	v_cvt_pk_bf16_f32 v60, v64, v67
	ds_write_b32 v118, v60 offset:12144
	ds_read_b128 v[60:63], v77 offset:32
	ds_read_b128 v[68:71], v77 offset:112
	s_waitcnt lgkmcnt(1)
	v_fma_f32 v60, -v9, v67, v60
	s_waitcnt lgkmcnt(0)
	v_fma_f32 v65, v9, v64, v68
	v_fmac_f32_e32 v60, v8, v64
	v_fmac_f32_e32 v65, v8, v67
	s_nop 0
	v_fma_f32 v61, -v9, v65, v61
	v_fma_f32 v66, v9, v60, v69
	v_cvt_pk_bf16_f32 v64, v60, v65
	v_fmac_f32_e32 v61, v8, v60
	v_fmac_f32_e32 v66, v8, v65
	ds_write_b32 v118, v64 offset:12416
	s_nop 0
	v_fma_f32 v62, -v9, v66, v62
	v_fma_f32 v64, v9, v61, v70
	v_cvt_pk_bf16_f32 v60, v61, v66
	v_fmac_f32_e32 v62, v8, v61
	v_fmac_f32_e32 v64, v8, v66
	ds_write_b32 v118, v60 offset:12688
	s_nop 0
	v_fma_f32 v68, -v9, v64, v63
	v_fmac_f32_e32 v71, v9, v62
	v_cvt_pk_bf16_f32 v60, v62, v64
	v_fmac_f32_e32 v68, v8, v62
	v_fmac_f32_e32 v71, v8, v64
	ds_write_b32 v118, v60 offset:12960
	s_nop 0
	v_cvt_pk_bf16_f32 v60, v68, v71
	ds_write_b32 v118, v60 offset:13232
	ds_read_b128 v[60:63], v77 offset:48
	ds_read_b128 v[64:67], v77 offset:128
	s_waitcnt lgkmcnt(1)
	v_fma_f32 v60, -v9, v71, v60
	s_waitcnt lgkmcnt(0)
	v_fma_f32 v64, v9, v68, v64
	v_fmac_f32_e32 v60, v8, v68
	v_fmac_f32_e32 v64, v8, v71
	s_nop 0
	v_fma_f32 v61, -v9, v64, v61
	v_fma_f32 v65, v9, v60, v65
	v_cvt_pk_bf16_f32 v68, v60, v64
	v_fmac_f32_e32 v61, v8, v60
	v_fmac_f32_e32 v65, v8, v64
	ds_write_b32 v118, v68 offset:13504
	v_mfma_f32_16x16x32_bf16 v[68:71], v[56:59], v[40:43], 0
	v_fma_f32 v62, -v9, v65, v62
	v_fma_f32 v64, v9, v61, v66
	v_cvt_pk_bf16_f32 v60, v61, v65
	v_fmac_f32_e32 v62, v8, v61
	v_fmac_f32_e32 v64, v8, v65
	ds_write_b32 v118, v60 offset:13776
	v_mfma_f32_16x16x32_bf16 v[40:43], v[20:23], v[40:43], 0
	v_fmac_f32_e32 v67, v9, v62
	v_cvt_pk_bf16_f32 v60, v62, v64
	v_fma_f32 v66, -v9, v64, v63
	v_fmac_f32_e32 v67, v8, v64
	v_or_b32_e32 v64, 16, v110
	v_fmac_f32_e32 v66, v8, v62
	v_ashrrev_i32_e32 v65, 31, v64
	ds_write_b32 v118, v60 offset:14048
	v_lshlrev_b64 v[114:115], 13, v[64:65]
	v_cvt_pk_bf16_f32 v60, v66, v67
	ds_write_b32 v118, v60 offset:14320
	v_lshl_add_u64 v[114:115], v[10:11], 0, v[114:115]
	ds_read_b128 v[60:63], v119 offset:10240
	ds_read_b128 v[136:139], v119 offset:10304
	s_waitcnt lgkmcnt(1)
	v_mfma_f32_16x16x32_bf16 v[60:63], v[60:63], v[16:19], 0
	ds_read_b128 v[140:143], v119 offset:10368
	v_or_b32_e32 v114, 17, v110
	v_ashrrev_i32_e32 v115, 31, v114
	s_waitcnt lgkmcnt(1)
	v_mfma_f32_16x16x32_bf16 v[60:63], v[136:139], v[12:15], v[60:63]
	ds_read_b128 v[136:139], v119 offset:10432
	s_waitcnt vmcnt(15)
	v_lshlrev_b32_e32 v65, 16, v156
	s_waitcnt lgkmcnt(1)
	v_mfma_f32_16x16x32_bf16 v[60:63], v[140:143], v[4:7], v[60:63]
	s_waitcnt lgkmcnt(0)
	v_mfma_f32_16x16x32_bf16 v[60:63], v[136:139], v[0:3], v[60:63]
	v_lshlrev_b64 v[136:137], 13, v[114:115]
	v_lshl_add_u64 v[136:137], v[10:11], 0, v[136:137]
	s_nop 5
	v_fma_f32 v60, v123, v65, v60
	v_mul_f32_e32 v65, 0x3d372713, v60
	v_mul_f32_e32 v65, v60, v65
	v_fma_f32 v65, v60, v65, v60
	v_mul_f32_e32 v65, 0xbfcc422a, v65
	v_mul_f32_e32 v65, 0x3fb8aa3b, v65
	v_exp_f32_e32 v109, v65
	v_mad_i64_i32 v[64:65], s[38:39], v64, s56, v[112:113]
	v_add_f32_e32 v109, 1.0, v109
	v_div_scale_f32 v111, s[38:39], v109, v109, v60
	v_rcp_f32_e32 v115, v111
	v_div_scale_f32 v138, vcc, v60, v109, v60
	v_fma_f32 v139, -v111, v115, 1.0
	v_fmac_f32_e32 v115, v139, v115
	v_mul_f32_e32 v139, v138, v115
	v_fma_f32 v140, -v111, v139, v138
	v_fmac_f32_e32 v139, v140, v115
	v_fma_f32 v111, -v111, v139, v138
	v_div_fmas_f32 v111, v111, v115, v139
	v_div_fixup_f32 v60, v111, v109, v60
	v_cvt_pk_bf16_f32 v60, v60, s0
	global_store_short v[64:65], v60, off
	v_or_b32_e32 v60, 18, v110
	v_mfma_f32_16x16x32_bf16 v[136:139], v[56:59], v[36:39], 0
	s_waitcnt vmcnt(15)
	v_lshlrev_b32_e32 v64, 16, v157
	v_fma_f32 v109, v123, v64, v61
	v_mul_f32_e32 v61, 0x3d372713, v109
	v_mul_f32_e32 v61, v109, v61
	v_fma_f32 v61, v109, v61, v109
	v_mul_f32_e32 v61, 0xbfcc422a, v61
	v_mul_f32_e32 v61, 0x3fb8aa3b, v61
	v_exp_f32_e32 v111, v61
	v_ashrrev_i32_e32 v61, 31, v60
	v_mad_i64_i32 v[64:65], s[38:39], v114, s56, v[112:113]
	v_lshlrev_b64 v[114:115], 13, v[60:61]
	v_add_f32_e32 v61, 1.0, v111
	v_div_scale_f32 v111, s[38:39], v61, v61, v109
	v_rcp_f32_e32 v140, v111
	v_div_scale_f32 v141, vcc, v109, v61, v109
	v_lshl_add_u64 v[114:115], v[10:11], 0, v[114:115]
	v_fma_f32 v142, -v111, v140, 1.0
	v_fmac_f32_e32 v140, v142, v140
	v_mul_f32_e32 v142, v141, v140
	v_fma_f32 v143, -v111, v142, v141
	v_fmac_f32_e32 v142, v143, v140
	v_fma_f32 v111, -v111, v142, v141
	v_div_fmas_f32 v111, v111, v140, v142
	v_div_fixup_f32 v61, v111, v61, v109
	v_cvt_pk_bf16_f32 v61, v61, s0
	global_store_short v[64:65], v61, off
	v_or_b32_e32 v64, 19, v110
	v_ashrrev_i32_e32 v65, 31, v64
	v_lshlrev_b64 v[114:115], 13, v[64:65]
	v_lshl_add_u64 v[114:115], v[10:11], 0, v[114:115]
	v_mfma_f32_16x16x32_bf16 v[140:143], v[56:59], v[32:35], 0
	s_waitcnt vmcnt(15)
	v_lshlrev_b32_e32 v61, 16, v158
	v_fma_f32 v62, v123, v61, v62
	v_mul_f32_e32 v61, 0x3d372713, v62
	v_mul_f32_e32 v61, v62, v61
	v_fma_f32 v61, v62, v61, v62
	v_mul_f32_e32 v61, 0xbfcc422a, v61
	v_mul_f32_e32 v61, 0x3fb8aa3b, v61
	v_exp_f32_e32 v109, v61
	v_mad_i64_i32 v[60:61], s[38:39], v60, s56, v[112:113]
	v_mfma_f32_16x16x32_bf16 v[36:39], v[20:23], v[36:39], 0
	v_add_f32_e32 v65, 1.0, v109
	v_div_scale_f32 v109, s[38:39], v65, v65, v62
	v_rcp_f32_e32 v111, v109
	v_div_scale_f32 v144, vcc, v62, v65, v62
	v_mfma_f32_16x16x32_bf16 v[32:35], v[20:23], v[32:35], 0
	v_fma_f32 v145, -v109, v111, 1.0
	v_fmac_f32_e32 v111, v145, v111
	v_mul_f32_e32 v145, v144, v111
	v_fma_f32 v146, -v109, v145, v144
	v_fmac_f32_e32 v145, v146, v111
	v_fma_f32 v109, -v109, v145, v144
	v_div_fmas_f32 v109, v109, v111, v145
	v_div_fixup_f32 v62, v109, v65, v62
	v_cvt_pk_bf16_f32 v62, v62, s0
	global_store_short v[60:61], v62, off
	v_mfma_f32_16x16x32_bf16 v[144:147], v[56:59], v[28:31], 0
	s_waitcnt vmcnt(15)
	v_lshlrev_b32_e32 v60, 16, v159
	v_fmac_f32_e32 v63, v123, v60
	v_mul_f32_e32 v60, 0x3d372713, v63
	v_mul_f32_e32 v60, v63, v60
	v_fma_f32 v60, v63, v60, v63
	v_mul_f32_e32 v60, 0xbfcc422a, v60
	v_mul_f32_e32 v60, 0x3fb8aa3b, v60
	v_exp_f32_e32 v60, v60
	v_mfma_f32_16x16x32_bf16 v[56:59], v[56:59], v[24:27], 0
	v_add_f32_e32 v62, 1.0, v60
	v_div_scale_f32 v65, s[38:39], v62, v62, v63
	v_rcp_f32_e32 v109, v65
	v_mad_i64_i32 v[60:61], s[38:39], v64, s56, v[112:113]
	v_div_scale_f32 v64, vcc, v63, v62, v63
	v_fma_f32 v111, -v65, v109, 1.0
	v_fmac_f32_e32 v109, v111, v109
	v_mul_f32_e32 v111, v64, v109
	v_fma_f32 v114, -v65, v111, v64
	v_fmac_f32_e32 v111, v114, v109
	v_fma_f32 v64, -v65, v111, v64
	v_div_fmas_f32 v64, v64, v109, v111
	v_div_fixup_f32 v62, v64, v62, v63
	v_cvt_pk_bf16_f32 v62, v62, s0
	global_store_short v[60:61], v62, off
	ds_write_b128 v73, v[124:127]
	ds_write_b128 v73, v[128:131] offset:1280
	ds_write_b128 v73, v[132:135] offset:2560
	ds_write_b128 v73, v[68:71] offset:3840
	ds_write_b128 v73, v[136:139] offset:5120
	ds_write_b128 v73, v[140:143] offset:6400
	ds_write_b128 v73, v[144:147] offset:7680
	ds_write_b128 v73, v[56:59] offset:8960
	ds_read_b128 v[60:63], v77
	ds_read_b128 v[56:59], v77 offset:80
	v_mfma_f32_16x16x32_bf16 v[28:31], v[20:23], v[28:31], 0
	s_waitcnt lgkmcnt(1)
	v_fma_f32 v60, -v9, v67, v60
	s_waitcnt lgkmcnt(0)
	v_fma_f32 v56, v9, v66, v56
	v_fmac_f32_e32 v60, v8, v66
	v_fmac_f32_e32 v56, v8, v67
	v_mfma_f32_16x16x32_bf16 v[20:23], v[20:23], v[24:27], 0
	v_fma_f32 v61, -v9, v56, v61
	v_fma_f32 v57, v9, v60, v57
	v_cvt_pk_bf16_f32 v64, v60, v56
	v_fmac_f32_e32 v61, v8, v60
	v_fmac_f32_e32 v57, v8, v56
	ds_write_b32 v118, v64 offset:10240
	s_nop 0
	v_fma_f32 v60, -v9, v57, v62
	v_fma_f32 v58, v9, v61, v58
	v_cvt_pk_bf16_f32 v56, v61, v57
	v_fmac_f32_e32 v60, v8, v61
	v_fmac_f32_e32 v58, v8, v57
	ds_write_b32 v118, v56 offset:10512
	s_nop 0
	v_fma_f32 v57, -v9, v58, v63
	v_fmac_f32_e32 v59, v9, v60
	v_cvt_pk_bf16_f32 v56, v60, v58
	v_fmac_f32_e32 v57, v8, v60
	v_fmac_f32_e32 v59, v8, v58
	ds_write_b32 v118, v56 offset:10784
	s_nop 0
	v_cvt_pk_bf16_f32 v56, v57, v59
	ds_write_b32 v118, v56 offset:11056
	ds_read_b128 v[64:67], v77 offset:16
	ds_read_b128 v[60:63], v77 offset:96
	s_waitcnt lgkmcnt(1)
	v_fma_f32 v56, -v9, v59, v64
	s_waitcnt lgkmcnt(0)
	v_fma_f32 v58, v9, v57, v60
	v_fmac_f32_e32 v56, v8, v57
	v_fmac_f32_e32 v58, v8, v59
	s_nop 0
	v_fma_f32 v59, -v9, v58, v65
	v_fma_f32 v60, v9, v56, v61
	v_cvt_pk_bf16_f32 v57, v56, v58
	v_fmac_f32_e32 v59, v8, v56
	v_fmac_f32_e32 v60, v8, v58
	ds_write_b32 v118, v57 offset:11328
	s_nop 0
	v_fma_f32 v57, -v9, v60, v66
	v_fma_f32 v58, v9, v59, v62
	v_cvt_pk_bf16_f32 v56, v59, v60
	v_fmac_f32_e32 v57, v8, v59
	v_fmac_f32_e32 v58, v8, v60
	ds_write_b32 v118, v56 offset:11600
	s_nop 0
	v_fma_f32 v60, -v9, v58, v67
	v_fmac_f32_e32 v63, v9, v57
	v_cvt_pk_bf16_f32 v56, v57, v58
	v_fmac_f32_e32 v60, v8, v57
	v_fmac_f32_e32 v63, v8, v58
	ds_write_b32 v118, v56 offset:11872
	s_nop 0
	v_cvt_pk_bf16_f32 v56, v60, v63
	ds_write_b32 v118, v56 offset:12144
	ds_read_b128 v[56:59], v77 offset:32
	ds_read_b128 v[64:67], v77 offset:112
	s_waitcnt lgkmcnt(1)
	v_fma_f32 v56, -v9, v63, v56
	s_waitcnt lgkmcnt(0)
	v_fma_f32 v61, v9, v60, v64
	v_fmac_f32_e32 v56, v8, v60
	v_fmac_f32_e32 v61, v8, v63
	s_nop 0
	v_fma_f32 v57, -v9, v61, v57
	v_fma_f32 v62, v9, v56, v65
	v_cvt_pk_bf16_f32 v60, v56, v61
	v_fmac_f32_e32 v57, v8, v56
	v_fmac_f32_e32 v62, v8, v61
	ds_write_b32 v118, v60 offset:12416
	s_nop 0
	v_fma_f32 v58, -v9, v62, v58
	v_fma_f32 v60, v9, v57, v66
	v_cvt_pk_bf16_f32 v56, v57, v62
	v_fmac_f32_e32 v58, v8, v57
	v_fmac_f32_e32 v60, v8, v62
	ds_write_b32 v118, v56 offset:12688
	s_nop 0
	v_fma_f32 v64, -v9, v60, v59
	v_fmac_f32_e32 v67, v9, v58
	v_cvt_pk_bf16_f32 v56, v58, v60
	v_fmac_f32_e32 v64, v8, v58
	v_fmac_f32_e32 v67, v8, v60
	ds_write_b32 v118, v56 offset:12960
	s_nop 0
	v_cvt_pk_bf16_f32 v56, v64, v67
	ds_write_b32 v118, v56 offset:13232
	ds_read_b128 v[56:59], v77 offset:48
	ds_read_b128 v[60:63], v77 offset:128
	s_waitcnt lgkmcnt(1)
	v_fma_f32 v56, -v9, v67, v56
	s_waitcnt lgkmcnt(0)
	v_fma_f32 v60, v9, v64, v60
	v_fmac_f32_e32 v56, v8, v64
	v_fmac_f32_e32 v60, v8, v67
	s_nop 0
	v_fma_f32 v57, -v9, v60, v57
	v_fma_f32 v61, v9, v56, v61
	v_cvt_pk_bf16_f32 v64, v56, v60
	v_fmac_f32_e32 v57, v8, v56
	v_fmac_f32_e32 v61, v8, v60
	ds_write_b32 v118, v64 offset:13504
	s_nop 0
	v_fma_f32 v58, -v9, v61, v58
	v_fma_f32 v60, v9, v57, v62
	v_cvt_pk_bf16_f32 v56, v57, v61
	v_fmac_f32_e32 v58, v8, v57
	v_fmac_f32_e32 v60, v8, v61
	ds_write_b32 v118, v56 offset:13776
	s_nop 0
	v_fma_f32 v62, -v9, v60, v59
	v_fmac_f32_e32 v63, v9, v58
	v_cvt_pk_bf16_f32 v56, v58, v60
	v_fmac_f32_e32 v62, v8, v58
	v_fmac_f32_e32 v63, v8, v60
	ds_write_b32 v118, v56 offset:14048
	v_or_b32_e32 v60, 32, v110
	v_cvt_pk_bf16_f32 v56, v62, v63
	ds_write_b32 v118, v56 offset:14320
	ds_read_b128 v[56:59], v119 offset:10240
	ds_read_b128 v[64:67], v119 offset:10304
	s_waitcnt lgkmcnt(1)
	v_mfma_f32_16x16x32_bf16 v[56:59], v[56:59], v[16:19], 0
	v_ashrrev_i32_e32 v61, 31, v60
	ds_read_b128 v[68:71], v119 offset:10368
	s_waitcnt lgkmcnt(1)
	v_mfma_f32_16x16x32_bf16 v[56:59], v[64:67], v[12:15], v[56:59]
	v_lshlrev_b64 v[64:65], 13, v[60:61]
	v_lshl_add_u64 v[114:115], v[10:11], 0, v[64:65]
	ds_read_b128 v[64:67], v119 offset:10432
	s_waitcnt lgkmcnt(1)
	v_mfma_f32_16x16x32_bf16 v[56:59], v[68:71], v[4:7], v[56:59]
	v_or_b32_e32 v68, 33, v110
	v_ashrrev_i32_e32 v69, 31, v68
	s_waitcnt vmcnt(15)
	v_lshlrev_b32_e32 v61, 16, v160
	s_waitcnt lgkmcnt(0)
	v_mfma_f32_16x16x32_bf16 v[56:59], v[64:67], v[0:3], v[56:59]
	v_lshlrev_b64 v[64:65], 13, v[68:69]
	v_lshl_add_u64 v[64:65], v[10:11], 0, v[64:65]
	s_nop 5
	v_fma_f32 v56, v123, v61, v56
	v_mul_f32_e32 v61, 0x3d372713, v56
	v_mul_f32_e32 v61, v56, v61
	v_fma_f32 v61, v56, v61, v56
	v_mul_f32_e32 v61, 0xbfcc422a, v61
	v_mul_f32_e32 v61, 0x3fb8aa3b, v61
	v_exp_f32_e32 v66, v61
	v_mad_i64_i32 v[60:61], s[38:39], v60, s56, v[112:113]
	v_add_f32_e32 v66, 1.0, v66
	v_div_scale_f32 v67, s[38:39], v66, v66, v56
	v_rcp_f32_e32 v69, v67
	v_div_scale_f32 v70, vcc, v56, v66, v56
	v_fma_f32 v71, -v67, v69, 1.0
	v_fmac_f32_e32 v69, v71, v69
	v_mul_f32_e32 v71, v70, v69
	v_fma_f32 v109, -v67, v71, v70
	v_fmac_f32_e32 v71, v109, v69
	v_fma_f32 v67, -v67, v71, v70
	v_div_fmas_f32 v67, v67, v69, v71
	v_div_fixup_f32 v56, v67, v66, v56
	v_cvt_pk_bf16_f32 v56, v56, s0
	global_store_short v[60:61], v56, off
	v_or_b32_e32 v56, 34, v110
	s_waitcnt vmcnt(15)
	v_lshlrev_b32_e32 v60, 16, v161
	v_fma_f32 v66, v123, v60, v57
	v_mul_f32_e32 v57, 0x3d372713, v66
	v_mul_f32_e32 v57, v66, v57
	v_fma_f32 v57, v66, v57, v66
	v_mul_f32_e32 v57, 0xbfcc422a, v57
	v_mul_f32_e32 v57, 0x3fb8aa3b, v57
	v_exp_f32_e32 v67, v57
	v_ashrrev_i32_e32 v57, 31, v56
	v_lshlrev_b64 v[64:65], 13, v[56:57]
	v_mad_i64_i32 v[60:61], s[38:39], v68, s56, v[112:113]
	v_add_f32_e32 v57, 1.0, v67
	v_div_scale_f32 v67, s[38:39], v57, v57, v66
	v_rcp_f32_e32 v68, v67
	v_div_scale_f32 v69, vcc, v66, v57, v66
	v_lshl_add_u64 v[64:65], v[10:11], 0, v[64:65]
	v_fma_f32 v70, -v67, v68, 1.0
	v_fmac_f32_e32 v68, v70, v68
	v_mul_f32_e32 v70, v69, v68
	v_fma_f32 v71, -v67, v70, v69
	v_fmac_f32_e32 v70, v71, v68
	v_fma_f32 v67, -v67, v70, v69
	v_div_fmas_f32 v67, v67, v68, v70
	v_div_fixup_f32 v57, v67, v57, v66
	v_cvt_pk_bf16_f32 v57, v57, s0
	global_store_short v[60:61], v57, off
	v_or_b32_e32 v60, 35, v110
	v_ashrrev_i32_e32 v61, 31, v60
	v_lshlrev_b64 v[64:65], 13, v[60:61]
	v_lshl_add_u64 v[64:65], v[10:11], 0, v[64:65]
	v_mad_i64_i32 v[24:25], s[38:39], v60, s56, v[112:113]
	s_waitcnt vmcnt(15)
	v_lshlrev_b32_e32 v57, 16, v162
	v_fma_f32 v58, v123, v57, v58
	v_mul_f32_e32 v57, 0x3d372713, v58
	v_mul_f32_e32 v57, v58, v57
	v_fma_f32 v57, v58, v57, v58
	v_mul_f32_e32 v57, 0xbfcc422a, v57
	v_mul_f32_e32 v57, 0x3fb8aa3b, v57
	v_exp_f32_e32 v66, v57
	v_mad_i64_i32 v[56:57], s[38:39], v56, s56, v[112:113]
	v_add_f32_e32 v61, 1.0, v66
	v_div_scale_f32 v66, s[38:39], v61, v61, v58
	v_rcp_f32_e32 v67, v66
	v_div_scale_f32 v68, vcc, v58, v61, v58
	v_fma_f32 v69, -v66, v67, 1.0
	v_fmac_f32_e32 v67, v69, v67
	v_mul_f32_e32 v69, v68, v67
	v_fma_f32 v70, -v66, v69, v68
	v_fmac_f32_e32 v69, v70, v67
	v_fma_f32 v66, -v66, v69, v68
	v_div_fmas_f32 v66, v66, v67, v69
	v_div_fixup_f32 v58, v66, v61, v58
	v_cvt_pk_bf16_f32 v58, v58, s0
	global_store_short v[56:57], v58, off
	s_waitcnt vmcnt(15)
	v_lshlrev_b32_e32 v56, 16, v163
	v_fmac_f32_e32 v59, v123, v56
	v_mul_f32_e32 v56, 0x3d372713, v59
	v_mul_f32_e32 v56, v59, v56
	v_fma_f32 v56, v59, v56, v59
	v_mul_f32_e32 v56, 0xbfcc422a, v56
	v_mul_f32_e32 v56, 0x3fb8aa3b, v56
	v_exp_f32_e32 v56, v56
	s_nop 0
	v_add_f32_e32 v26, 1.0, v56
	v_div_scale_f32 v27, s[38:39], v26, v26, v59
	v_rcp_f32_e32 v56, v27
	v_div_scale_f32 v57, vcc, v59, v26, v59
	v_fma_f32 v58, -v27, v56, 1.0
	v_fmac_f32_e32 v56, v58, v56
	v_mul_f32_e32 v58, v57, v56
	v_fma_f32 v60, -v27, v58, v57
	v_fmac_f32_e32 v58, v60, v56
	v_fma_f32 v27, -v27, v58, v57
	v_div_fmas_f32 v27, v27, v56, v58
	v_div_fixup_f32 v26, v27, v26, v59
	v_cvt_pk_bf16_f32 v26, v26, s0
	global_store_short v[24:25], v26, off
	ds_write_b128 v73, v[52:55]
	ds_write_b128 v73, v[48:51] offset:1280
	ds_write_b128 v73, v[44:47] offset:2560
	ds_write_b128 v73, v[40:43] offset:3840
	ds_write_b128 v73, v[36:39] offset:5120
	ds_write_b128 v73, v[32:35] offset:6400
	ds_write_b128 v73, v[28:31] offset:7680
	ds_write_b128 v73, v[20:23] offset:8960
	ds_read_b128 v[20:23], v77
	ds_read_b128 v[24:27], v77 offset:80
	s_waitcnt lgkmcnt(1)
	v_fma_f32 v20, -v9, v63, v20
	s_waitcnt lgkmcnt(0)
	v_fma_f32 v24, v9, v62, v24
	v_fmac_f32_e32 v20, v8, v62
	v_fmac_f32_e32 v24, v8, v63
	s_nop 0
	v_fma_f32 v21, -v9, v24, v21
	v_fma_f32 v25, v9, v20, v25
	v_cvt_pk_bf16_f32 v28, v20, v24
	v_fmac_f32_e32 v21, v8, v20
	v_fmac_f32_e32 v25, v8, v24
	ds_write_b32 v118, v28 offset:10240
	s_nop 0
	v_fma_f32 v22, -v9, v25, v22
	v_fma_f32 v24, v9, v21, v26
	v_cvt_pk_bf16_f32 v20, v21, v25
	v_fmac_f32_e32 v22, v8, v21
	v_fmac_f32_e32 v24, v8, v25
	ds_write_b32 v118, v20 offset:10512
	s_nop 0
	v_fma_f32 v25, -v9, v24, v23
	v_fmac_f32_e32 v27, v9, v22
	v_cvt_pk_bf16_f32 v20, v22, v24
	v_fmac_f32_e32 v25, v8, v22
	v_fmac_f32_e32 v27, v8, v24
	ds_write_b32 v118, v20 offset:10784
	s_nop 0
	v_cvt_pk_bf16_f32 v20, v25, v27
	ds_write_b32 v118, v20 offset:11056
	ds_read_b128 v[20:23], v77 offset:16
	ds_read_b128 v[28:31], v77 offset:96
	s_waitcnt lgkmcnt(1)
	v_fma_f32 v20, -v9, v27, v20
	s_waitcnt lgkmcnt(0)
	v_fma_f32 v24, v9, v25, v28
	v_fmac_f32_e32 v20, v8, v25
	v_fmac_f32_e32 v24, v8, v27
	s_nop 0
	v_fma_f32 v21, -v9, v24, v21
	v_fma_f32 v26, v9, v20, v29
	v_cvt_pk_bf16_f32 v25, v20, v24
	v_fmac_f32_e32 v21, v8, v20
	v_fmac_f32_e32 v26, v8, v24
	ds_write_b32 v118, v25 offset:11328
	s_nop 0
	v_fma_f32 v22, -v9, v26, v22
	v_fma_f32 v24, v9, v21, v30
	v_cvt_pk_bf16_f32 v20, v21, v26
	v_fmac_f32_e32 v22, v8, v21
	v_fmac_f32_e32 v24, v8, v26
	ds_write_b32 v118, v20 offset:11600
	s_nop 0
	v_fma_f32 v28, -v9, v24, v23
	v_fmac_f32_e32 v31, v9, v22
	v_cvt_pk_bf16_f32 v20, v22, v24
	v_fmac_f32_e32 v28, v8, v22
	v_fmac_f32_e32 v31, v8, v24
	ds_write_b32 v118, v20 offset:11872
	s_nop 0
	v_cvt_pk_bf16_f32 v20, v28, v31
	ds_write_b32 v118, v20 offset:12144
	ds_read_b128 v[20:23], v77 offset:32
	ds_read_b128 v[24:27], v77 offset:112
	s_waitcnt lgkmcnt(1)
	v_fma_f32 v20, -v9, v31, v20
	s_waitcnt lgkmcnt(0)
	v_fma_f32 v24, v9, v28, v24
	v_fmac_f32_e32 v20, v8, v28
	v_fmac_f32_e32 v24, v8, v31
	s_nop 0
	v_fma_f32 v21, -v9, v24, v21
	v_fma_f32 v25, v9, v20, v25
	v_cvt_pk_bf16_f32 v28, v20, v24
	v_fmac_f32_e32 v21, v8, v20
	v_fmac_f32_e32 v25, v8, v24
	ds_write_b32 v118, v28 offset:12416
	s_nop 0
	v_fma_f32 v22, -v9, v25, v22
	v_fma_f32 v24, v9, v21, v26
	v_cvt_pk_bf16_f32 v20, v21, v25
	v_fmac_f32_e32 v22, v8, v21
	v_fmac_f32_e32 v24, v8, v25
	ds_write_b32 v118, v20 offset:12688
	s_nop 0
	v_fma_f32 v25, -v9, v24, v23
	v_fmac_f32_e32 v27, v9, v22
	v_cvt_pk_bf16_f32 v20, v22, v24
	v_fmac_f32_e32 v25, v8, v22
	v_fmac_f32_e32 v27, v8, v24
	ds_write_b32 v118, v20 offset:12960
	s_nop 0
	v_cvt_pk_bf16_f32 v20, v25, v27
	ds_write_b32 v118, v20 offset:13232
	ds_read_b128 v[28:31], v77 offset:48
	ds_read_b128 v[20:23], v77 offset:128
	s_waitcnt lgkmcnt(1)
	v_fma_f32 v24, -v9, v27, v28
	s_waitcnt lgkmcnt(0)
	v_fma_f32 v20, v9, v25, v20
	v_fmac_f32_e32 v24, v8, v25
	v_fmac_f32_e32 v20, v8, v27
	s_nop 0
	v_fma_f32 v26, -v9, v20, v29
	v_fma_f32 v21, v9, v24, v21
	v_cvt_pk_bf16_f32 v25, v24, v20
	v_fmac_f32_e32 v26, v8, v24
	v_fmac_f32_e32 v21, v8, v20
	ds_write_b32 v118, v25 offset:13504
	s_nop 0
	v_fma_f32 v24, -v9, v21, v30
	v_fma_f32 v25, v9, v26, v22
	v_cvt_pk_bf16_f32 v20, v26, v21
	v_fmac_f32_e32 v24, v8, v26
	v_fmac_f32_e32 v25, v8, v21
	ds_write_b32 v118, v20 offset:13776
	s_nop 0
	v_fma_f32 v22, -v9, v25, v31
	v_fmac_f32_e32 v23, v9, v24
	v_cvt_pk_bf16_f32 v20, v24, v25
	v_fmac_f32_e32 v22, v8, v24
	v_fmac_f32_e32 v23, v8, v25
	ds_write_b32 v118, v20 offset:14048
	s_nop 0
	v_cvt_pk_bf16_f32 v8, v22, v23
	v_mov_b32_e32 v254, v22
	v_mov_b32_e32 v255, v23
	ds_write_b32 v118, v8 offset:14320
	ds_read_b128 v[24:27], v119 offset:10240
	ds_read_b128 v[28:31], v119 offset:10304
	s_waitcnt lgkmcnt(1)
	v_mfma_f32_16x16x32_bf16 v[16:19], v[24:27], v[16:19], 0
	v_or_b32_e32 v8, 48, v110
	v_ashrrev_i32_e32 v9, 31, v8
	ds_read_b128 v[24:27], v119 offset:10368
	s_waitcnt lgkmcnt(1)
	v_mfma_f32_16x16x32_bf16 v[12:15], v[28:31], v[12:15], v[16:19]
	s_nop 2
	v_lshlrev_b64 v[16:17], 13, v[8:9]
	v_lshl_add_u64 v[20:21], v[10:11], 0, v[16:17]
	ds_read_b128 v[16:19], v119 offset:10432
	s_waitcnt lgkmcnt(1)
	v_mfma_f32_16x16x32_bf16 v[4:7], v[24:27], v[4:7], v[12:15]
	s_waitcnt lgkmcnt(0)
	v_mfma_f32_16x16x32_bf16 v[0:3], v[16:19], v[0:3], v[4:7]
	s_nop 0
	v_or_b32_e32 v12, 49, v110
	v_ashrrev_i32_e32 v13, 31, v12
	s_nop 2
	v_lshlrev_b64 v[6:7], 13, v[12:13]
	v_lshl_add_u64 v[6:7], v[10:11], 0, v[6:7]
	s_waitcnt vmcnt(15)
	v_lshlrev_b32_e32 v4, 16, v164
	v_fma_f32 v0, v123, v4, v0
	v_mul_f32_e32 v4, 0x3d372713, v0
	v_mul_f32_e32 v4, v0, v4
	v_fma_f32 v4, v0, v4, v0
	v_mul_f32_e32 v4, 0xbfcc422a, v4
	v_mul_f32_e32 v4, 0x3fb8aa3b, v4
	v_exp_f32_e32 v9, v4
	v_mad_i64_i32 v[4:5], s[38:39], v8, s56, v[112:113]
	v_add_f32_e32 v8, 1.0, v9
	v_div_scale_f32 v9, s[38:39], v8, v8, v0
	v_rcp_f32_e32 v13, v9
	v_div_scale_f32 v14, vcc, v0, v8, v0
	v_fma_f32 v15, -v9, v13, 1.0
	v_fmac_f32_e32 v13, v15, v13
	v_mul_f32_e32 v15, v14, v13
	v_fma_f32 v16, -v9, v15, v14
	v_fmac_f32_e32 v15, v16, v13
	v_fma_f32 v9, -v9, v15, v14
	v_div_fmas_f32 v9, v9, v13, v15
	v_div_fixup_f32 v0, v9, v8, v0
	v_cvt_pk_bf16_f32 v0, v0, s0
	global_store_short v[4:5], v0, off
	v_or_b32_e32 v0, 50, v110
	s_waitcnt vmcnt(15)
	v_lshlrev_b32_e32 v4, 16, v165
	v_fma_f32 v8, v123, v4, v1
	v_mul_f32_e32 v1, 0x3d372713, v8
	v_mul_f32_e32 v1, v8, v1
	v_fma_f32 v1, v8, v1, v8
	v_mul_f32_e32 v1, 0xbfcc422a, v1
	v_mul_f32_e32 v1, 0x3fb8aa3b, v1
	v_exp_f32_e32 v9, v1
	v_ashrrev_i32_e32 v1, 31, v0
	v_lshlrev_b64 v[6:7], 13, v[0:1]
	v_mad_i64_i32 v[4:5], s[38:39], v12, s56, v[112:113]
	v_add_f32_e32 v1, 1.0, v9
	v_div_scale_f32 v9, s[38:39], v1, v1, v8
	v_rcp_f32_e32 v12, v9
	v_div_scale_f32 v13, vcc, v8, v1, v8
	v_lshl_add_u64 v[6:7], v[10:11], 0, v[6:7]
	v_fma_f32 v14, -v9, v12, 1.0
	v_fmac_f32_e32 v12, v14, v12
	v_mul_f32_e32 v14, v13, v12
	v_fma_f32 v15, -v9, v14, v13
	v_fmac_f32_e32 v14, v15, v12
	v_fma_f32 v9, -v9, v14, v13
	v_div_fmas_f32 v9, v9, v12, v14
	v_div_fixup_f32 v1, v9, v1, v8
	v_cvt_pk_bf16_f32 v1, v1, s0
	global_store_short v[4:5], v1, off
	v_or_b32_e32 v4, 51, v110
	v_ashrrev_i32_e32 v5, 31, v4
	v_lshlrev_b64 v[6:7], 13, v[4:5]
	v_lshl_add_u64 v[6:7], v[10:11], 0, v[6:7]
	s_waitcnt vmcnt(15)
	v_lshlrev_b32_e32 v1, 16, v166
	v_fma_f32 v2, v123, v1, v2
	v_mul_f32_e32 v1, 0x3d372713, v2
	v_mul_f32_e32 v1, v2, v1
	v_fma_f32 v1, v2, v1, v2
	v_mul_f32_e32 v1, 0xbfcc422a, v1
	v_mul_f32_e32 v1, 0x3fb8aa3b, v1
	v_exp_f32_e32 v8, v1
	v_mad_i64_i32 v[0:1], s[38:39], v0, s56, v[112:113]
	v_add_f32_e32 v5, 1.0, v8
	v_div_scale_f32 v8, s[38:39], v5, v5, v2
	v_rcp_f32_e32 v9, v8
	v_div_scale_f32 v10, vcc, v2, v5, v2
	v_fma_f32 v11, -v8, v9, 1.0
	v_fmac_f32_e32 v9, v11, v9
	v_mul_f32_e32 v11, v10, v9
	v_fma_f32 v12, -v8, v11, v10
	v_fmac_f32_e32 v11, v12, v9
	v_fma_f32 v8, -v8, v11, v10
	v_div_fmas_f32 v8, v8, v9, v11
	v_div_fixup_f32 v2, v8, v5, v2
	v_cvt_pk_bf16_f32 v2, v2, s0
	global_store_short v[0:1], v2, off
	s_waitcnt vmcnt(15)
	v_lshlrev_b32_e32 v0, 16, v167
	v_fmac_f32_e32 v3, v123, v0
	v_mul_f32_e32 v0, 0x3d372713, v3
	v_mul_f32_e32 v0, v3, v0
	v_fma_f32 v0, v3, v0, v3
	v_mul_f32_e32 v0, 0xbfcc422a, v0
	v_mul_f32_e32 v0, 0x3fb8aa3b, v0
	v_exp_f32_e32 v0, v0
	s_nop 0
	v_add_f32_e32 v2, 1.0, v0
	v_div_scale_f32 v5, s[38:39], v2, v2, v3
	v_rcp_f32_e32 v6, v5
	v_mad_i64_i32 v[0:1], s[38:39], v4, s56, v[112:113]
	v_div_scale_f32 v4, vcc, v3, v2, v3
	v_fma_f32 v7, -v5, v6, 1.0
	v_fmac_f32_e32 v6, v7, v6
	v_mul_f32_e32 v7, v4, v6
	v_fma_f32 v8, -v5, v7, v4
	v_fmac_f32_e32 v7, v8, v6
	v_fma_f32 v4, -v5, v7, v4
	v_div_fmas_f32 v4, v4, v6, v7
	v_div_fixup_f32 v2, v4, v2, v3
	v_cvt_pk_bf16_f32 v2, v2, s0
	global_store_short v[0:1], v2, off
	v_cmp_eq_u32_e32 vcc, 63, v122
	s_and_saveexec_b64 s[38:39], vcc
	s_cbranch_execz .LBB0_380
	v_mad_i32_i24 v0, v121, s46, v108
	v_ashrrev_i32_e32 v1, 31, v0
	v_lshlrev_b64 v[0:1], 9, v[0:1]
	v_lshl_add_u64 v[0:1], v[100:101], 0, v[0:1]
	global_store_dwordx2 v[0:1], v[22:23], off
	s_branch .LBB0_380
